# attention unit prologue: K/V tile loads issued before the gate_b row loads, tile waits counted (vmcnt 5/4) so the key loop starts as soon as K/V land
# baseline (speedup 1.0000x reference)
; #define LAS __attribute__((address_space(3)))
;     ...
;     const int tid = tid_, lane = tid & 63, wid = __builtin_amdgcn_readfirstlane(tid >> 6), r32 = lane & 31, hi = lane >> 5;
;     const size_t rowbase = (size_t)b * SEQ;
;     const int q0 = qb * 256, qw = q0 + wid * 32;
;     bf16x8 qr[4];
;     { const bf16* qp = UGQ + (rowbase + qw + r32) * 2048 + 1024 + h * HD + hi * 8;
; #pragma unroll
;       for (int d0 = 0; d0 < 4; ++d0) qr[d0] = *(const bf16x8*)(qp + d0 * 16); }
;     f32x16 o0, o1;
; #pragma unroll
;     for (int r = 0; r < 16; ++r) { o0[r] = 0.f; o1[r] = 0.f; }
;     float C = 1.f; int alive = 1;
;     volatile LAS unsigned* aflag = (volatile LAS unsigned*)(lds + RING_BYTES);
;     const int NT = 4 * (qb + 1);
;     const int lkey = lane, lch = wid;
;     const int kk = lkey & 31, slot = (lkey & 32) | (8 * ((kk >> 2) & 3) + 4 * (kk >> 4) + (kk & 3));
;     const bf16* kg = Kb + (rowbase + lkey) * 1024 + h * HD + lch * 8;
;     const bf16* vg = Vb + (rowbase + lkey) * 1024 + h * HD + lch * 8;
;     u32x4 kreg, vreg;
;     kreg = *(const u32x4*)(kg + (size_t)(NT - 1) * 64 * 1024); vreg = *(const u32x4*)(vg + (size_t)(NT - 1) * 64 * 1024);
;     ...
;     AT_WRITE(0);
;     __syncthreads();
;     ...
;         const u32x4 gw_ = *(const u32x4*)(GBb + tok * 1024 + h * HD + ch * 8);
.LBB0_457:
	s_xor_b64 s[28:29], s[4:5], -1
	s_and_b64 s[4:5], s[4:5], exec
	v_readlane_b32 s1, v255, 48
	v_mov_b32_e32 v104, v232
	s_cselect_b32 s6, s1, s0
	v_readlane_b32 s12, v254, 58
	v_readfirstlane_b32 s1, v104
	s_ashr_i32 s33, s1, 6
	s_lshl_b32 s1, s6, 8
	s_lshl_b32 s24, s33, 5
	s_add_i32 s24, s24, s1
	s_ashr_i32 s4, s24, 31
	s_add_u32 s10, s18, s24
	v_and_b32_e32 v106, 31, v104
	s_addc_u32 s11, s19, s4
	v_or_b32_e32 v0, s10, v106
	v_mov_b32_e32 v1, s11
	v_bfe_u32 v4, v104, 5, 1
	v_lshlrev_b64 v[0:1], 12, v[0:1]
	v_lshl_add_u64 v[0:1], s[30:31], 0, v[0:1]
	v_lshlrev_b32_e32 v64, 4, v4
	v_lshl_add_u64 v[0:1], v[0:1], 0, v[64:65]
	global_load_dwordx4 v[66:69], v[0:1], off offset:2048
	global_load_dwordx4 v[70:73], v[0:1], off offset:2080
	global_load_dwordx4 v[74:77], v[0:1], off offset:2112
	global_load_dwordx4 v[78:81], v[0:1], off offset:2144
	v_lshlrev_b32_e32 v0, 1, v104
	v_lshrrev_b32_e32 v1, 2, v104
	v_and_b32_e32 v105, 63, v104
	v_and_b32_e32 v0, 24, v0
	v_and_b32_e32 v1, 4, v1
	v_and_b32_e32 v2, 35, v104
	v_or3_b32 v5, v2, v1, v0
	v_or_b32_e32 v0, s18, v105
	v_mov_b32_e32 v1, s19
	v_readlane_b32 s4, v255, 49
	v_lshlrev_b64 v[0:1], 11, v[0:1]
	v_readlane_b32 s5, v255, 50
	s_lshl_b32 s7, s6, 19
	v_readlane_b32 s13, v254, 59
	v_lshl_add_u64 v[2:3], s[4:5], 0, v[0:1]
	s_lshl_b32 s4, s33, 3
	s_ashr_i32 s5, s4, 31
	s_lshl_b64 s[4:5], s[4:5], 1
	v_lshl_add_u64 v[0:1], s[8:9], 0, v[0:1]
	v_lshl_add_u64 v[2:3], v[2:3], 0, s[4:5]
	v_lshl_add_u64 v[0:1], v[0:1], 0, s[4:5]
	s_mov_b32 s21, s13
	s_or_b32 s20, s7, 0x60000
	v_lshl_add_u64 v[2:3], v[2:3], 0, s[20:21]
	v_lshl_add_u64 v[0:1], v[0:1], 0, s[20:21]
	global_load_dwordx4 v[82:85], v[2:3], off
	global_load_dwordx4 v[86:89], v[0:1], off
	v_lshlrev_b32_e32 v114, 3, v104
	v_lshrrev_b32_e32 v116, 3, v105
	v_and_b32_e32 v114, 56, v114
	v_or_b32_e32 v116, s10, v116
	v_mov_b32_e32 v117, s11
	v_lshlrev_b32_e32 v114, 1, v114
	v_mov_b32_e32 v115, 0
	v_lshlrev_b64 v[116:117], 11, v[116:117]
	v_lshl_add_u64 v[114:115], s[14:15], 0, v[114:115]
	s_mov_b64 s[100:101], 0x4000
	v_lshl_add_u64 v[114:115], v[114:115], 0, v[116:117]
	global_load_dwordx4 v[128:131], v[114:115], off
	v_lshl_add_u64 v[116:117], v[114:115], 0, s[100:101]
	global_load_dwordx4 v[132:135], v[116:117], off
	v_lshl_add_u64 v[116:117], s[100:101], 1, v[114:115]
	global_load_dwordx4 v[136:139], v[116:117], off
	v_lshl_add_u64 v[116:117], v[116:117], 0, s[100:101]
	global_load_dwordx4 v[164:167], v[116:117], off
	s_lshl_b32 s25, s6, 2
	s_lshl_b32 s6, s33, 10
	v_writelane_b32 v254, s12, 58
	s_add_i32 s20, s6, 0
	s_mul_i32 s6, s33, 0x480
	v_writelane_b32 v254, s13, 59
	s_add_i32 s6, s6, 0
	v_lshl_add_u32 v108, v105, 1, s6
	s_lshl_b32 s6, s33, 2
	v_readlane_b32 s12, v254, 57
	s_add_i32 s25, s25, 4
	s_add_i32 s26, s12, s6
	v_lshlrev_b32_e32 v0, 10, v4
	v_lshlrev_b32_e32 v1, 4, v106
	v_add3_u32 v111, 0, v0, v1
	v_mul_u32_u24_e32 v0, 0x90, v106
	v_and_b32_e32 v1, 32, v104
	s_add_u32 s4, s4, s7
	v_add3_u32 v112, 0, v0, v1
	v_lshlrev_b32_e32 v0, 11, v105
	v_mov_b32_e32 v1, v65
	s_addc_u32 s5, s5, 0
	v_lshl_add_u64 v[0:1], s[4:5], 0, v[0:1]
	v_mov_b32_e32 v14, v65
	v_mov_b32_e32 v15, v65
	v_lshl_add_u32 v107, v5, 4, s20
	v_lshl_add_u64 v[90:91], s[34:35], 0, v[0:1]
	v_lshl_add_u64 v[92:93], s[2:3], 0, v[0:1]
	v_mov_b32_e32 v0, v65
	v_mov_b32_e32 v1, v65
	v_mov_b32_e32 v2, v65
	v_mov_b32_e32 v3, v65
	v_mov_b32_e32 v4, v65
	v_mov_b32_e32 v5, v65
	v_mov_b32_e32 v6, v65
	v_mov_b32_e32 v7, v65
	v_mov_b32_e32 v8, v65
	v_mov_b32_e32 v9, v65
	v_mov_b32_e32 v10, v65
	v_mov_b32_e32 v11, v65
	v_mov_b32_e32 v12, v65
	v_mov_b32_e32 v13, v65
	v_mov_b64_e32 v[30:31], v[14:15]
	v_or_b32_e32 v109, s24, v106
	v_lshl_add_u32 v110, v105, 2, s12
	v_cmp_gt_u32_e64 s[36:37], 32, v105
	s_mov_b32 s6, 0
	v_cmp_eq_u32_e64 s[38:39], 0, v105
	v_cmp_gt_u32_e64 s[40:41], 8, v105
	s_or_b32 s27, s1, 0xc0
	v_mov_b32_e32 v95, 1.0
	v_mov_b32_e32 v32, 1
	v_mov_b64_e32 v[28:29], v[12:13]
	v_mov_b64_e32 v[26:27], v[10:11]
	v_mov_b64_e32 v[24:25], v[8:9]
	v_mov_b64_e32 v[22:23], v[6:7]
	v_mov_b64_e32 v[20:21], v[4:5]
	v_mov_b64_e32 v[18:19], v[2:3]
	v_mov_b64_e32 v[16:17], v[0:1]
	s_waitcnt vmcnt(5)
	ds_write_b128 v107, v[82:85]
	s_waitcnt vmcnt(4)
	ds_write_b16 v108, v86 offset:16384
	ds_write_b16_d16_hi v108, v86 offset:16528
	ds_write_b16 v108, v87 offset:16672
	ds_write_b16_d16_hi v108, v87 offset:16816
	ds_write_b16 v108, v88 offset:16960
	ds_write_b16_d16_hi v108, v88 offset:17104
	ds_write_b16 v108, v89 offset:17248
	ds_write_b16_d16_hi v108, v89 offset:17392
	s_waitcnt lgkmcnt(0)
	s_barrier
	s_cmpk_eq_i32 s27, 0xffc0
	s_cbranch_scc0 .LBB0_459
